# v11 + P7 final epilogue de-serialised: the 16 gate loads hoisted in two batches of 8 into free registers, counted vmcnt(7) waits instead of vmcnt(0) per iteration
# speedup vs baseline: 1.0030x; 1.0030x over previous
.LBB0_1229:
	s_cmp_lg_u32 s39, 0
	s_cselect_b64 s[52:53], -1, 0
	s_lshl_b32 s19, s54, 8
	v_add_u32_e32 v4, s19, v1
	s_and_b64 vcc, exec, s[52:53]
	v_lshl_or_b32 v154, s38, 8, v168
	v_or_b32_e32 v160, 16, v4
	v_or_b32_e32 v152, 32, v4
	v_or_b32_e32 v150, 48, v4
	s_cbranch_vccz .LBB0_1237
	v_mov_b64_e32 v[166:167], s[46:47]
	v_mad_i64_i32 v[156:157], s[38:39], v4, s73, v[166:167]
	v_ashrrev_i32_e32 v155, 31, v154
	v_lshl_add_u64 v[174:175], v[156:157], 0, s[14:15]
	v_lshlrev_b64 v[156:157], 1, v[154:155]
	v_lshl_add_u64 v[158:159], v[174:175], 0, v[156:157]
	s_mov_b32 s76, 0xa4000
	s_mov_b32 s77, 0
	s_mov_b32 s78, 0x520000
	s_mov_b32 s79, 0
	v_mov_b64_e32 v[238:239], v[158:159]
	global_load_dwordx4 v[202:205], v[158:159], off
	global_load_dwordx4 v[206:209], v[158:159], off offset:256
	v_lshl_add_u64 v[234:235], v[158:159], 0, s[76:77]
	global_load_dwordx4 v[210:213], v[234:235], off
	global_load_dwordx4 v[214:217], v[234:235], off offset:256
	v_lshl_add_u64 v[236:237], v[234:235], 0, s[76:77]
	global_load_dwordx4 v[218:221], v[236:237], off
	global_load_dwordx4 v[222:225], v[236:237], off offset:256
	v_lshl_add_u64 v[234:235], v[236:237], 0, s[76:77]
	global_load_dwordx4 v[226:229], v[234:235], off
	global_load_dwordx4 v[230:233], v[234:235], off offset:256
	v_ashrrev_i32_e32 v5, 31, v4
	v_lshlrev_b64 v[176:177], 13, v[4:5]
	v_or_b32_e32 v158, 0x80, v154
	v_ashrrev_i32_e32 v159, 31, v158
	v_lshl_add_u64 v[176:177], s[28:29], 0, v[176:177]
	v_lshlrev_b64 v[158:159], 1, v[158:159]
	v_lshl_add_u64 v[176:177], v[176:177], 0, v[156:157]
	v_lshl_add_u64 v[174:175], v[174:175], 0, v[158:159]
	s_waitcnt vmcnt(7)
	v_lshlrev_b32_e32 v3, 16, v202
	v_and_b32_e32 v5, 0xffff0000, v202
	v_lshlrev_b32_e32 v151, 16, v203
	v_and_b32_e32 v153, 0xffff0000, v203
	v_lshlrev_b32_e32 v155, 16, v204
	v_and_b32_e32 v161, 0xffff0000, v204
	v_lshlrev_b32_e32 v170, 16, v205
	v_and_b32_e32 v171, 0xffff0000, v205
	v_mul_f32_e32 v3, 0xbfb8aa3b, v3
	v_mul_f32_e32 v5, 0xbfb8aa3b, v5
	v_mul_f32_e32 v151, 0xbfb8aa3b, v151
	v_mul_f32_e32 v153, 0xbfb8aa3b, v153
	v_mul_f32_e32 v155, 0xbfb8aa3b, v155
	v_mul_f32_e32 v161, 0xbfb8aa3b, v161
	v_mul_f32_e32 v170, 0xbfb8aa3b, v170
	v_mul_f32_e32 v171, 0xbfb8aa3b, v171
	v_exp_f32_e32 v3, v3
	v_exp_f32_e32 v5, v5
	v_exp_f32_e32 v151, v151
	v_exp_f32_e32 v153, v153
	v_exp_f32_e32 v155, v155
	v_exp_f32_e32 v161, v161
	v_exp_f32_e32 v170, v170
	v_exp_f32_e32 v171, v171
	v_add_f32_e32 v3, 1.0, v3
	v_add_f32_e32 v5, 1.0, v5
	v_add_f32_e32 v151, 1.0, v151
	v_add_f32_e32 v153, 1.0, v153
	v_add_f32_e32 v155, 1.0, v155
	v_add_f32_e32 v161, 1.0, v161
	v_add_f32_e32 v179, 1.0, v170
	v_add_f32_e32 v181, 1.0, v171
	v_rcp_f32_e32 v170, v3
	v_rcp_f32_e32 v171, v5
	v_rcp_f32_e32 v172, v151
	v_rcp_f32_e32 v173, v153
	v_rcp_f32_e32 v178, v155
	v_rcp_f32_e32 v180, v179
	v_rcp_f32_e32 v181, v181
	v_rcp_f32_e32 v179, v161
	v_pk_mul_f32 v[172:173], v[132:133], v[172:173]
	v_pk_mul_f32 v[170:171], v[130:131], v[170:171]
	v_pk_mul_f32 v[180:181], v[128:129], v[180:181]
	v_pk_mul_f32 v[178:179], v[126:127], v[178:179]
	v_cvt_pk_bf16_f32 v170, v170, v171
	v_cvt_pk_bf16_f32 v171, v172, v173
	s_nop 0
	v_cvt_pk_bf16_f32 v172, v178, v179
	v_cvt_pk_bf16_f32 v173, v180, v181
	global_store_dwordx4 v[176:177], v[170:173], off
	v_mad_i64_i32 v[174:175], s[38:39], v160, s73, v[166:167]
	v_lshl_add_u64 v[174:175], v[174:175], 0, s[14:15]
	v_lshl_add_u64 v[178:179], v[174:175], 0, v[156:157]
	v_lshl_add_u64 v[174:175], v[174:175], 0, v[158:159]
	s_waitcnt vmcnt(7)
	v_lshlrev_b32_e32 v3, 16, v206
	v_and_b32_e32 v5, 0xffff0000, v206
	v_lshlrev_b32_e32 v151, 16, v207
	v_and_b32_e32 v153, 0xffff0000, v207
	v_lshlrev_b32_e32 v155, 16, v208
	v_and_b32_e32 v161, 0xffff0000, v208
	v_lshlrev_b32_e32 v170, 16, v209
	v_and_b32_e32 v171, 0xffff0000, v209
	v_mul_f32_e32 v3, 0xbfb8aa3b, v3
	v_mul_f32_e32 v5, 0xbfb8aa3b, v5
	v_mul_f32_e32 v151, 0xbfb8aa3b, v151
	v_mul_f32_e32 v153, 0xbfb8aa3b, v153
	v_mul_f32_e32 v155, 0xbfb8aa3b, v155
	v_mul_f32_e32 v161, 0xbfb8aa3b, v161
	v_mul_f32_e32 v170, 0xbfb8aa3b, v170
	v_mul_f32_e32 v171, 0xbfb8aa3b, v171
	v_exp_f32_e32 v3, v3
	v_exp_f32_e32 v5, v5
	v_exp_f32_e32 v151, v151
	v_exp_f32_e32 v153, v153
	v_exp_f32_e32 v155, v155
	v_exp_f32_e32 v161, v161
	v_exp_f32_e32 v170, v170
	v_exp_f32_e32 v171, v171
	v_add_f32_e32 v3, 1.0, v3
	v_add_f32_e32 v5, 1.0, v5
	v_add_f32_e32 v151, 1.0, v151
	v_add_f32_e32 v153, 1.0, v153
	v_add_f32_e32 v155, 1.0, v155
	v_add_f32_e32 v161, 1.0, v161
	v_add_f32_e32 v181, 1.0, v170
	v_add_f32_e32 v183, 1.0, v171
	v_rcp_f32_e32 v170, v3
	v_rcp_f32_e32 v171, v5
	v_rcp_f32_e32 v172, v151
	v_rcp_f32_e32 v173, v153
	v_rcp_f32_e32 v180, v155
	v_rcp_f32_e32 v182, v181
	v_rcp_f32_e32 v183, v183
	v_rcp_f32_e32 v181, v161
	v_pk_mul_f32 v[172:173], v[100:101], v[172:173]
	v_pk_mul_f32 v[170:171], v[98:99], v[170:171]
	v_pk_mul_f32 v[182:183], v[96:97], v[182:183]
	v_pk_mul_f32 v[180:181], v[94:95], v[180:181]
	v_cvt_pk_bf16_f32 v170, v170, v171
	v_cvt_pk_bf16_f32 v171, v172, v173
	v_ashrrev_i32_e32 v161, 31, v160
	v_cvt_pk_bf16_f32 v172, v180, v181
	v_cvt_pk_bf16_f32 v173, v182, v183
	global_store_dwordx4 v[176:177], v[170:173], off offset:256
	v_lshlrev_b64 v[176:177], 13, v[160:161]
	v_lshl_add_u64 v[176:177], s[28:29], 0, v[176:177]
	v_lshl_add_u64 v[176:177], v[176:177], 0, v[156:157]
	s_waitcnt vmcnt(7)
	v_lshlrev_b32_e32 v3, 16, v210
	v_and_b32_e32 v5, 0xffff0000, v210
	v_lshlrev_b32_e32 v151, 16, v211
	v_and_b32_e32 v153, 0xffff0000, v211
	v_lshlrev_b32_e32 v155, 16, v212
	v_and_b32_e32 v161, 0xffff0000, v212
	v_lshlrev_b32_e32 v170, 16, v213
	v_and_b32_e32 v171, 0xffff0000, v213
	v_mul_f32_e32 v3, 0xbfb8aa3b, v3
	v_mul_f32_e32 v5, 0xbfb8aa3b, v5
	v_mul_f32_e32 v151, 0xbfb8aa3b, v151
	v_mul_f32_e32 v153, 0xbfb8aa3b, v153
	v_mul_f32_e32 v155, 0xbfb8aa3b, v155
	v_mul_f32_e32 v161, 0xbfb8aa3b, v161
	v_mul_f32_e32 v170, 0xbfb8aa3b, v170
	v_mul_f32_e32 v171, 0xbfb8aa3b, v171
	v_exp_f32_e32 v3, v3
	v_exp_f32_e32 v5, v5
	v_exp_f32_e32 v151, v151
	v_exp_f32_e32 v153, v153
	v_exp_f32_e32 v155, v155
	v_exp_f32_e32 v161, v161
	v_exp_f32_e32 v170, v170
	v_exp_f32_e32 v171, v171
	v_add_f32_e32 v3, 1.0, v3
	v_add_f32_e32 v5, 1.0, v5
	v_add_f32_e32 v151, 1.0, v151
	v_add_f32_e32 v153, 1.0, v153
	v_add_f32_e32 v155, 1.0, v155
	v_add_f32_e32 v161, 1.0, v161
	v_add_f32_e32 v179, 1.0, v170
	v_add_f32_e32 v181, 1.0, v171
	v_rcp_f32_e32 v170, v3
	v_rcp_f32_e32 v171, v5
	v_rcp_f32_e32 v172, v151
	v_rcp_f32_e32 v173, v153
	v_rcp_f32_e32 v178, v155
	v_rcp_f32_e32 v180, v179
	v_rcp_f32_e32 v181, v181
	v_rcp_f32_e32 v179, v161
	v_pk_mul_f32 v[172:173], v[124:125], v[172:173]
	v_pk_mul_f32 v[170:171], v[122:123], v[170:171]
	v_pk_mul_f32 v[180:181], v[120:121], v[180:181]
	v_pk_mul_f32 v[178:179], v[118:119], v[178:179]
	v_cvt_pk_bf16_f32 v170, v170, v171
	v_cvt_pk_bf16_f32 v171, v172, v173
	s_nop 0
	v_cvt_pk_bf16_f32 v172, v178, v179
	v_cvt_pk_bf16_f32 v173, v180, v181
	global_store_dwordx4 v[176:177], v[170:173], off
	v_mad_i64_i32 v[174:175], s[38:39], v152, s73, v[166:167]
	v_lshl_add_u64 v[174:175], v[174:175], 0, s[14:15]
	v_lshl_add_u64 v[178:179], v[174:175], 0, v[156:157]
	v_lshl_add_u64 v[174:175], v[174:175], 0, v[158:159]
	s_waitcnt vmcnt(7)
	v_lshlrev_b32_e32 v3, 16, v214
	v_and_b32_e32 v5, 0xffff0000, v214
	v_lshlrev_b32_e32 v151, 16, v215
	v_and_b32_e32 v153, 0xffff0000, v215
	v_lshlrev_b32_e32 v155, 16, v216
	v_and_b32_e32 v161, 0xffff0000, v216
	v_lshlrev_b32_e32 v170, 16, v217
	v_and_b32_e32 v171, 0xffff0000, v217
	v_mul_f32_e32 v3, 0xbfb8aa3b, v3
	v_mul_f32_e32 v5, 0xbfb8aa3b, v5
	v_mul_f32_e32 v151, 0xbfb8aa3b, v151
	v_mul_f32_e32 v153, 0xbfb8aa3b, v153
	v_mul_f32_e32 v155, 0xbfb8aa3b, v155
	v_mul_f32_e32 v161, 0xbfb8aa3b, v161
	v_mul_f32_e32 v170, 0xbfb8aa3b, v170
	v_mul_f32_e32 v171, 0xbfb8aa3b, v171
	v_exp_f32_e32 v3, v3
	v_exp_f32_e32 v5, v5
	v_exp_f32_e32 v151, v151
	v_exp_f32_e32 v153, v153
	v_exp_f32_e32 v155, v155
	v_exp_f32_e32 v161, v161
	v_exp_f32_e32 v170, v170
	v_exp_f32_e32 v171, v171
	v_add_f32_e32 v3, 1.0, v3
	v_add_f32_e32 v5, 1.0, v5
	v_add_f32_e32 v151, 1.0, v151
	v_add_f32_e32 v153, 1.0, v153
	v_add_f32_e32 v155, 1.0, v155
	v_add_f32_e32 v161, 1.0, v161
	v_add_f32_e32 v181, 1.0, v170
	v_add_f32_e32 v183, 1.0, v171
	v_rcp_f32_e32 v170, v3
	v_rcp_f32_e32 v171, v5
	v_rcp_f32_e32 v172, v151
	v_rcp_f32_e32 v173, v153
	v_rcp_f32_e32 v180, v155
	v_rcp_f32_e32 v182, v181
	v_rcp_f32_e32 v183, v183
	v_rcp_f32_e32 v181, v161
	v_pk_mul_f32 v[172:173], v[92:93], v[172:173]
	v_pk_mul_f32 v[170:171], v[90:91], v[170:171]
	v_pk_mul_f32 v[182:183], v[88:89], v[182:183]
	v_pk_mul_f32 v[180:181], v[86:87], v[180:181]
	v_cvt_pk_bf16_f32 v170, v170, v171
	v_cvt_pk_bf16_f32 v171, v172, v173
	v_ashrrev_i32_e32 v153, 31, v152
	v_cvt_pk_bf16_f32 v172, v180, v181
	v_cvt_pk_bf16_f32 v173, v182, v183
	global_store_dwordx4 v[176:177], v[170:173], off offset:256
	v_lshlrev_b64 v[176:177], 13, v[152:153]
	v_lshl_add_u64 v[176:177], s[28:29], 0, v[176:177]
	v_lshl_add_u64 v[176:177], v[176:177], 0, v[156:157]
	s_waitcnt vmcnt(7)
	v_lshlrev_b32_e32 v3, 16, v218
	v_and_b32_e32 v5, 0xffff0000, v218
	v_lshlrev_b32_e32 v151, 16, v219
	v_and_b32_e32 v153, 0xffff0000, v219
	v_lshlrev_b32_e32 v155, 16, v220
	v_and_b32_e32 v161, 0xffff0000, v220
	v_lshlrev_b32_e32 v170, 16, v221
	v_and_b32_e32 v171, 0xffff0000, v221
	v_mul_f32_e32 v3, 0xbfb8aa3b, v3
	v_mul_f32_e32 v5, 0xbfb8aa3b, v5
	v_mul_f32_e32 v151, 0xbfb8aa3b, v151
	v_mul_f32_e32 v153, 0xbfb8aa3b, v153
	v_mul_f32_e32 v155, 0xbfb8aa3b, v155
	v_mul_f32_e32 v161, 0xbfb8aa3b, v161
	v_mul_f32_e32 v170, 0xbfb8aa3b, v170
	v_mul_f32_e32 v171, 0xbfb8aa3b, v171
	v_exp_f32_e32 v3, v3
	v_exp_f32_e32 v5, v5
	v_exp_f32_e32 v151, v151
	v_exp_f32_e32 v153, v153
	v_exp_f32_e32 v155, v155
	v_exp_f32_e32 v161, v161
	v_exp_f32_e32 v170, v170
	v_exp_f32_e32 v171, v171
	v_add_f32_e32 v3, 1.0, v3
	v_add_f32_e32 v5, 1.0, v5
	v_add_f32_e32 v151, 1.0, v151
	v_add_f32_e32 v153, 1.0, v153
	v_add_f32_e32 v155, 1.0, v155
	v_add_f32_e32 v161, 1.0, v161
	v_add_f32_e32 v179, 1.0, v170
	v_add_f32_e32 v181, 1.0, v171
	v_rcp_f32_e32 v170, v3
	v_rcp_f32_e32 v171, v5
	v_rcp_f32_e32 v172, v151
	v_rcp_f32_e32 v173, v153
	v_rcp_f32_e32 v178, v155
	v_rcp_f32_e32 v180, v179
	v_rcp_f32_e32 v181, v181
	v_rcp_f32_e32 v179, v161
	v_pk_mul_f32 v[172:173], v[116:117], v[172:173]
	v_pk_mul_f32 v[170:171], v[114:115], v[170:171]
	v_pk_mul_f32 v[180:181], v[112:113], v[180:181]
	v_pk_mul_f32 v[178:179], v[110:111], v[178:179]
	v_cvt_pk_bf16_f32 v170, v170, v171
	v_cvt_pk_bf16_f32 v171, v172, v173
	s_nop 0
	v_cvt_pk_bf16_f32 v172, v178, v179
	v_cvt_pk_bf16_f32 v173, v180, v181
	global_store_dwordx4 v[176:177], v[170:173], off
	v_mad_i64_i32 v[174:175], s[38:39], v150, s73, v[166:167]
	v_lshl_add_u64 v[174:175], v[174:175], 0, s[14:15]
	v_lshl_add_u64 v[178:179], v[174:175], 0, v[156:157]
	v_lshl_add_u64 v[174:175], v[174:175], 0, v[158:159]
	s_waitcnt vmcnt(7)
	v_lshlrev_b32_e32 v3, 16, v222
	v_and_b32_e32 v5, 0xffff0000, v222
	v_lshlrev_b32_e32 v151, 16, v223
	v_and_b32_e32 v153, 0xffff0000, v223
	v_lshlrev_b32_e32 v155, 16, v224
	v_and_b32_e32 v161, 0xffff0000, v224
	v_lshlrev_b32_e32 v170, 16, v225
	v_and_b32_e32 v171, 0xffff0000, v225
	v_mul_f32_e32 v3, 0xbfb8aa3b, v3
	v_mul_f32_e32 v5, 0xbfb8aa3b, v5
	v_mul_f32_e32 v151, 0xbfb8aa3b, v151
	v_mul_f32_e32 v153, 0xbfb8aa3b, v153
	v_mul_f32_e32 v155, 0xbfb8aa3b, v155
	v_mul_f32_e32 v161, 0xbfb8aa3b, v161
	v_mul_f32_e32 v170, 0xbfb8aa3b, v170
	v_mul_f32_e32 v171, 0xbfb8aa3b, v171
	v_exp_f32_e32 v3, v3
	v_exp_f32_e32 v5, v5
	v_exp_f32_e32 v151, v151
	v_exp_f32_e32 v153, v153
	v_exp_f32_e32 v155, v155
	v_exp_f32_e32 v161, v161
	v_exp_f32_e32 v170, v170
	v_exp_f32_e32 v171, v171
	v_add_f32_e32 v3, 1.0, v3
	v_add_f32_e32 v5, 1.0, v5
	v_add_f32_e32 v151, 1.0, v151
	v_add_f32_e32 v153, 1.0, v153
	v_add_f32_e32 v155, 1.0, v155
	v_add_f32_e32 v161, 1.0, v161
	v_add_f32_e32 v181, 1.0, v170
	v_add_f32_e32 v183, 1.0, v171
	v_rcp_f32_e32 v170, v3
	v_rcp_f32_e32 v171, v5
	v_rcp_f32_e32 v172, v151
	v_rcp_f32_e32 v173, v153
	v_rcp_f32_e32 v180, v155
	v_rcp_f32_e32 v182, v181
	v_rcp_f32_e32 v183, v183
	v_rcp_f32_e32 v181, v161
	v_pk_mul_f32 v[172:173], v[84:85], v[172:173]
	v_pk_mul_f32 v[170:171], v[82:83], v[170:171]
	v_pk_mul_f32 v[182:183], v[80:81], v[182:183]
	v_pk_mul_f32 v[180:181], v[78:79], v[180:181]
	v_cvt_pk_bf16_f32 v170, v170, v171
	v_cvt_pk_bf16_f32 v171, v172, v173
	v_ashrrev_i32_e32 v151, 31, v150
	v_cvt_pk_bf16_f32 v172, v180, v181
	v_cvt_pk_bf16_f32 v173, v182, v183
	global_store_dwordx4 v[176:177], v[170:173], off offset:256
	v_lshlrev_b64 v[176:177], 13, v[150:151]
	v_lshl_add_u64 v[176:177], s[28:29], 0, v[176:177]
	v_lshl_add_u64 v[176:177], v[176:177], 0, v[156:157]
	s_waitcnt vmcnt(7)
	v_lshlrev_b32_e32 v3, 16, v226
	v_and_b32_e32 v5, 0xffff0000, v226
	v_lshlrev_b32_e32 v151, 16, v227
	v_and_b32_e32 v153, 0xffff0000, v227
	v_lshlrev_b32_e32 v155, 16, v228
	v_and_b32_e32 v161, 0xffff0000, v228
	v_lshlrev_b32_e32 v170, 16, v229
	v_and_b32_e32 v171, 0xffff0000, v229
	v_mul_f32_e32 v3, 0xbfb8aa3b, v3
	v_mul_f32_e32 v5, 0xbfb8aa3b, v5
	v_mul_f32_e32 v151, 0xbfb8aa3b, v151
	v_mul_f32_e32 v153, 0xbfb8aa3b, v153
	v_mul_f32_e32 v155, 0xbfb8aa3b, v155
	v_mul_f32_e32 v161, 0xbfb8aa3b, v161
	v_mul_f32_e32 v170, 0xbfb8aa3b, v170
	v_mul_f32_e32 v171, 0xbfb8aa3b, v171
	v_exp_f32_e32 v3, v3
	v_exp_f32_e32 v5, v5
	v_exp_f32_e32 v151, v151
	v_exp_f32_e32 v153, v153
	v_exp_f32_e32 v155, v155
	v_exp_f32_e32 v161, v161
	v_exp_f32_e32 v170, v170
	v_exp_f32_e32 v171, v171
	v_add_f32_e32 v3, 1.0, v3
	v_add_f32_e32 v5, 1.0, v5
	v_add_f32_e32 v151, 1.0, v151
	v_add_f32_e32 v153, 1.0, v153
	v_add_f32_e32 v155, 1.0, v155
	v_add_f32_e32 v161, 1.0, v161
	v_add_f32_e32 v179, 1.0, v170
	v_add_f32_e32 v181, 1.0, v171
	v_rcp_f32_e32 v170, v3
	v_rcp_f32_e32 v171, v5
	v_rcp_f32_e32 v172, v151
	v_rcp_f32_e32 v173, v153
	v_rcp_f32_e32 v178, v155
	v_rcp_f32_e32 v180, v179
	v_rcp_f32_e32 v181, v181
	v_rcp_f32_e32 v179, v161
	v_pk_mul_f32 v[172:173], v[108:109], v[172:173]
	v_pk_mul_f32 v[170:171], v[106:107], v[170:171]
	v_pk_mul_f32 v[180:181], v[104:105], v[180:181]
	v_pk_mul_f32 v[178:179], v[102:103], v[178:179]
	v_cvt_pk_bf16_f32 v170, v170, v171
	v_cvt_pk_bf16_f32 v171, v172, v173
	s_nop 0
	v_cvt_pk_bf16_f32 v172, v178, v179
	v_cvt_pk_bf16_f32 v173, v180, v181
	global_store_dwordx4 v[176:177], v[170:173], off
	v_add_u32_e32 v174, 0x80, v4
	v_mad_i64_i32 v[178:179], s[38:39], v174, s73, v[166:167]
	v_lshl_add_u64 v[178:179], v[178:179], 0, s[14:15]
	v_lshl_add_u64 v[180:181], v[178:179], 0, v[156:157]
	s_waitcnt vmcnt(7)
	v_lshlrev_b32_e32 v3, 16, v230
	v_and_b32_e32 v5, 0xffff0000, v230
	v_lshlrev_b32_e32 v151, 16, v231
	v_and_b32_e32 v153, 0xffff0000, v231
	v_lshlrev_b32_e32 v155, 16, v232
	v_and_b32_e32 v161, 0xffff0000, v232
	v_lshlrev_b32_e32 v170, 16, v233
	v_and_b32_e32 v171, 0xffff0000, v233
	v_mul_f32_e32 v3, 0xbfb8aa3b, v3
	v_mul_f32_e32 v5, 0xbfb8aa3b, v5
	v_mul_f32_e32 v151, 0xbfb8aa3b, v151
	v_mul_f32_e32 v153, 0xbfb8aa3b, v153
	v_mul_f32_e32 v155, 0xbfb8aa3b, v155
	v_mul_f32_e32 v161, 0xbfb8aa3b, v161
	v_mul_f32_e32 v170, 0xbfb8aa3b, v170
	v_mul_f32_e32 v171, 0xbfb8aa3b, v171
	v_exp_f32_e32 v3, v3
	v_exp_f32_e32 v5, v5
	v_exp_f32_e32 v151, v151
	v_exp_f32_e32 v153, v153
	v_exp_f32_e32 v155, v155
	v_exp_f32_e32 v161, v161
	v_exp_f32_e32 v170, v170
	v_exp_f32_e32 v171, v171
	v_add_f32_e32 v3, 1.0, v3
	v_add_f32_e32 v5, 1.0, v5
	v_add_f32_e32 v151, 1.0, v151
	v_add_f32_e32 v153, 1.0, v153
	v_add_f32_e32 v155, 1.0, v155
	v_add_f32_e32 v161, 1.0, v161
	v_add_f32_e32 v175, 1.0, v170
	v_add_f32_e32 v183, 1.0, v171
	v_rcp_f32_e32 v170, v3
	v_rcp_f32_e32 v171, v5
	v_rcp_f32_e32 v172, v151
	v_rcp_f32_e32 v173, v153
	v_rcp_f32_e32 v182, v155
	v_rcp_f32_e32 v184, v175
	v_rcp_f32_e32 v185, v183
	v_rcp_f32_e32 v183, v161
	v_pk_mul_f32 v[172:173], v[76:77], v[172:173]
	v_pk_mul_f32 v[170:171], v[74:75], v[170:171]
	v_pk_mul_f32 v[184:185], v[72:73], v[184:185]
	v_pk_mul_f32 v[182:183], v[70:71], v[182:183]
	v_cvt_pk_bf16_f32 v170, v170, v171
	v_cvt_pk_bf16_f32 v171, v172, v173
	v_ashrrev_i32_e32 v175, 31, v174
	v_cvt_pk_bf16_f32 v172, v182, v183
	v_cvt_pk_bf16_f32 v173, v184, v185
	global_store_dwordx4 v[176:177], v[170:173], off offset:256
	v_lshl_add_u64 v[240:241], v[238:239], 0, s[78:79]
	global_load_dwordx4 v[202:205], v[240:241], off
	global_load_dwordx4 v[206:209], v[240:241], off offset:256
	v_lshl_add_u64 v[234:235], v[240:241], 0, s[76:77]
	global_load_dwordx4 v[210:213], v[234:235], off
	global_load_dwordx4 v[214:217], v[234:235], off offset:256
	v_lshl_add_u64 v[236:237], v[234:235], 0, s[76:77]
	global_load_dwordx4 v[218:221], v[236:237], off
	global_load_dwordx4 v[222:225], v[236:237], off offset:256
	v_lshl_add_u64 v[234:235], v[236:237], 0, s[76:77]
	global_load_dwordx4 v[226:229], v[234:235], off
	global_load_dwordx4 v[230:233], v[234:235], off offset:256
	v_lshl_add_u64 v[176:177], v[178:179], 0, v[158:159]
	v_lshlrev_b64 v[174:175], 13, v[174:175]
	v_lshl_add_u64 v[174:175], s[28:29], 0, v[174:175]
	v_lshl_add_u64 v[174:175], v[174:175], 0, v[156:157]
	s_waitcnt vmcnt(7)
	v_lshlrev_b32_e32 v3, 16, v202
	v_and_b32_e32 v5, 0xffff0000, v202
	v_lshlrev_b32_e32 v151, 16, v203
	v_and_b32_e32 v153, 0xffff0000, v203
	v_lshlrev_b32_e32 v155, 16, v204
	v_and_b32_e32 v161, 0xffff0000, v204
	v_lshlrev_b32_e32 v170, 16, v205
	v_and_b32_e32 v171, 0xffff0000, v205
	v_mul_f32_e32 v3, 0xbfb8aa3b, v3
	v_mul_f32_e32 v5, 0xbfb8aa3b, v5
	v_mul_f32_e32 v151, 0xbfb8aa3b, v151
	v_mul_f32_e32 v153, 0xbfb8aa3b, v153
	v_mul_f32_e32 v155, 0xbfb8aa3b, v155
	v_mul_f32_e32 v161, 0xbfb8aa3b, v161
	v_mul_f32_e32 v170, 0xbfb8aa3b, v170
	v_mul_f32_e32 v171, 0xbfb8aa3b, v171
	v_exp_f32_e32 v3, v3
	v_exp_f32_e32 v5, v5
	v_exp_f32_e32 v151, v151
	v_exp_f32_e32 v153, v153
	v_exp_f32_e32 v155, v155
	v_exp_f32_e32 v161, v161
	v_exp_f32_e32 v170, v170
	v_exp_f32_e32 v171, v171
	v_add_f32_e32 v3, 1.0, v3
	v_add_f32_e32 v5, 1.0, v5
	v_add_f32_e32 v151, 1.0, v151
	v_add_f32_e32 v153, 1.0, v153
	v_add_f32_e32 v155, 1.0, v155
	v_add_f32_e32 v161, 1.0, v161
	v_add_f32_e32 v179, 1.0, v170
	v_add_f32_e32 v181, 1.0, v171
	v_rcp_f32_e32 v170, v3
	v_rcp_f32_e32 v171, v5
	v_rcp_f32_e32 v172, v151
	v_rcp_f32_e32 v173, v153
	v_rcp_f32_e32 v178, v155
	v_rcp_f32_e32 v180, v179
	v_rcp_f32_e32 v181, v181
	v_rcp_f32_e32 v179, v161
	v_pk_mul_f32 v[172:173], v[68:69], v[172:173]
	v_pk_mul_f32 v[170:171], v[66:67], v[170:171]
	v_pk_mul_f32 v[180:181], v[64:65], v[180:181]
	v_pk_mul_f32 v[178:179], v[62:63], v[178:179]
	v_cvt_pk_bf16_f32 v170, v170, v171
	v_cvt_pk_bf16_f32 v171, v172, v173
	s_nop 0
	v_cvt_pk_bf16_f32 v172, v178, v179
	v_cvt_pk_bf16_f32 v173, v180, v181
	global_store_dwordx4 v[174:175], v[170:173], off
	v_add_u32_e32 v176, 0x90, v4
	v_mad_i64_i32 v[178:179], s[38:39], v176, s73, v[166:167]
	v_lshl_add_u64 v[178:179], v[178:179], 0, s[14:15]
	v_lshl_add_u64 v[180:181], v[178:179], 0, v[156:157]
	s_waitcnt vmcnt(7)
	v_lshlrev_b32_e32 v3, 16, v206
	v_and_b32_e32 v5, 0xffff0000, v206
	v_lshlrev_b32_e32 v151, 16, v207
	v_and_b32_e32 v153, 0xffff0000, v207
	v_lshlrev_b32_e32 v155, 16, v208
	v_and_b32_e32 v161, 0xffff0000, v208
	v_lshlrev_b32_e32 v170, 16, v209
	v_and_b32_e32 v171, 0xffff0000, v209
	v_mul_f32_e32 v3, 0xbfb8aa3b, v3
	v_mul_f32_e32 v5, 0xbfb8aa3b, v5
	v_mul_f32_e32 v151, 0xbfb8aa3b, v151
	v_mul_f32_e32 v153, 0xbfb8aa3b, v153
	v_mul_f32_e32 v155, 0xbfb8aa3b, v155
	v_mul_f32_e32 v161, 0xbfb8aa3b, v161
	v_mul_f32_e32 v170, 0xbfb8aa3b, v170
	v_mul_f32_e32 v171, 0xbfb8aa3b, v171
	v_exp_f32_e32 v3, v3
	v_exp_f32_e32 v5, v5
	v_exp_f32_e32 v151, v151
	v_exp_f32_e32 v153, v153
	v_exp_f32_e32 v155, v155
	v_exp_f32_e32 v161, v161
	v_exp_f32_e32 v170, v170
	v_exp_f32_e32 v171, v171
	v_add_f32_e32 v3, 1.0, v3
	v_add_f32_e32 v5, 1.0, v5
	v_add_f32_e32 v151, 1.0, v151
	v_add_f32_e32 v153, 1.0, v153
	v_add_f32_e32 v155, 1.0, v155
	v_add_f32_e32 v161, 1.0, v161
	v_add_f32_e32 v177, 1.0, v170
	v_add_f32_e32 v183, 1.0, v171
	v_rcp_f32_e32 v170, v3
	v_rcp_f32_e32 v171, v5
	v_rcp_f32_e32 v172, v151
	v_rcp_f32_e32 v173, v153
	v_rcp_f32_e32 v182, v155
	v_rcp_f32_e32 v184, v177
	v_rcp_f32_e32 v185, v183
	v_rcp_f32_e32 v183, v161
	v_pk_mul_f32 v[172:173], v[36:37], v[172:173]
	v_pk_mul_f32 v[170:171], v[34:35], v[170:171]
	v_pk_mul_f32 v[184:185], v[32:33], v[184:185]
	v_pk_mul_f32 v[182:183], v[30:31], v[182:183]
	v_cvt_pk_bf16_f32 v170, v170, v171
	v_cvt_pk_bf16_f32 v171, v172, v173
	v_ashrrev_i32_e32 v177, 31, v176
	v_cvt_pk_bf16_f32 v172, v182, v183
	v_cvt_pk_bf16_f32 v173, v184, v185
	global_store_dwordx4 v[174:175], v[170:173], off offset:256
	v_lshlrev_b64 v[174:175], 13, v[176:177]
	v_lshl_add_u64 v[176:177], v[178:179], 0, v[158:159]
	v_lshl_add_u64 v[174:175], s[28:29], 0, v[174:175]
	v_lshl_add_u64 v[174:175], v[174:175], 0, v[156:157]
	s_waitcnt vmcnt(7)
	v_lshlrev_b32_e32 v3, 16, v210
	v_and_b32_e32 v5, 0xffff0000, v210
	v_lshlrev_b32_e32 v151, 16, v211
	v_and_b32_e32 v153, 0xffff0000, v211
	v_lshlrev_b32_e32 v155, 16, v212
	v_and_b32_e32 v161, 0xffff0000, v212
	v_lshlrev_b32_e32 v170, 16, v213
	v_and_b32_e32 v171, 0xffff0000, v213
	v_mul_f32_e32 v3, 0xbfb8aa3b, v3
	v_mul_f32_e32 v5, 0xbfb8aa3b, v5
	v_mul_f32_e32 v151, 0xbfb8aa3b, v151
	v_mul_f32_e32 v153, 0xbfb8aa3b, v153
	v_mul_f32_e32 v155, 0xbfb8aa3b, v155
	v_mul_f32_e32 v161, 0xbfb8aa3b, v161
	v_mul_f32_e32 v170, 0xbfb8aa3b, v170
	v_mul_f32_e32 v171, 0xbfb8aa3b, v171
	v_exp_f32_e32 v3, v3
	v_exp_f32_e32 v5, v5
	v_exp_f32_e32 v151, v151
	v_exp_f32_e32 v153, v153
	v_exp_f32_e32 v155, v155
	v_exp_f32_e32 v161, v161
	v_exp_f32_e32 v170, v170
	v_exp_f32_e32 v171, v171
	v_add_f32_e32 v3, 1.0, v3
	v_add_f32_e32 v5, 1.0, v5
	v_add_f32_e32 v151, 1.0, v151
	v_add_f32_e32 v153, 1.0, v153
	v_add_f32_e32 v155, 1.0, v155
	v_add_f32_e32 v161, 1.0, v161
	v_add_f32_e32 v179, 1.0, v170
	v_add_f32_e32 v181, 1.0, v171
	v_rcp_f32_e32 v170, v3
	v_rcp_f32_e32 v171, v5
	v_rcp_f32_e32 v172, v151
	v_rcp_f32_e32 v173, v153
	v_rcp_f32_e32 v178, v155
	v_rcp_f32_e32 v180, v179
	v_rcp_f32_e32 v181, v181
	v_rcp_f32_e32 v179, v161
	v_pk_mul_f32 v[172:173], v[60:61], v[172:173]
	v_pk_mul_f32 v[170:171], v[58:59], v[170:171]
	v_pk_mul_f32 v[180:181], v[56:57], v[180:181]
	v_pk_mul_f32 v[178:179], v[54:55], v[178:179]
	v_cvt_pk_bf16_f32 v170, v170, v171
	v_cvt_pk_bf16_f32 v171, v172, v173
	s_nop 0
	v_cvt_pk_bf16_f32 v172, v178, v179
	v_cvt_pk_bf16_f32 v173, v180, v181
	global_store_dwordx4 v[174:175], v[170:173], off
	v_add_u32_e32 v176, 0xa0, v4
	v_mad_i64_i32 v[178:179], s[38:39], v176, s73, v[166:167]
	v_lshl_add_u64 v[178:179], v[178:179], 0, s[14:15]
	v_lshl_add_u64 v[180:181], v[178:179], 0, v[156:157]
	s_waitcnt vmcnt(7)
	v_lshlrev_b32_e32 v3, 16, v214
	v_and_b32_e32 v5, 0xffff0000, v214
	v_lshlrev_b32_e32 v151, 16, v215
	v_and_b32_e32 v153, 0xffff0000, v215
	v_lshlrev_b32_e32 v155, 16, v216
	v_and_b32_e32 v161, 0xffff0000, v216
	v_lshlrev_b32_e32 v170, 16, v217
	v_and_b32_e32 v171, 0xffff0000, v217
	v_mul_f32_e32 v3, 0xbfb8aa3b, v3
	v_mul_f32_e32 v5, 0xbfb8aa3b, v5
	v_mul_f32_e32 v151, 0xbfb8aa3b, v151
	v_mul_f32_e32 v153, 0xbfb8aa3b, v153
	v_mul_f32_e32 v155, 0xbfb8aa3b, v155
	v_mul_f32_e32 v161, 0xbfb8aa3b, v161
	v_mul_f32_e32 v170, 0xbfb8aa3b, v170
	v_mul_f32_e32 v171, 0xbfb8aa3b, v171
	v_exp_f32_e32 v3, v3
	v_exp_f32_e32 v5, v5
	v_exp_f32_e32 v151, v151
	v_exp_f32_e32 v153, v153
	v_exp_f32_e32 v155, v155
	v_exp_f32_e32 v161, v161
	v_exp_f32_e32 v170, v170
	v_exp_f32_e32 v171, v171
	v_add_f32_e32 v3, 1.0, v3
	v_add_f32_e32 v5, 1.0, v5
	v_add_f32_e32 v151, 1.0, v151
	v_add_f32_e32 v153, 1.0, v153
	v_add_f32_e32 v155, 1.0, v155
	v_add_f32_e32 v161, 1.0, v161
	v_add_f32_e32 v177, 1.0, v170
	v_add_f32_e32 v183, 1.0, v171
	v_rcp_f32_e32 v170, v3
	v_rcp_f32_e32 v171, v5
	v_rcp_f32_e32 v172, v151
	v_rcp_f32_e32 v173, v153
	v_rcp_f32_e32 v182, v155
	v_rcp_f32_e32 v184, v177
	v_rcp_f32_e32 v185, v183
	v_rcp_f32_e32 v183, v161
	v_pk_mul_f32 v[172:173], v[28:29], v[172:173]
	v_pk_mul_f32 v[170:171], v[26:27], v[170:171]
	v_pk_mul_f32 v[184:185], v[24:25], v[184:185]
	v_pk_mul_f32 v[182:183], v[22:23], v[182:183]
	v_cvt_pk_bf16_f32 v170, v170, v171
	v_cvt_pk_bf16_f32 v171, v172, v173
	v_ashrrev_i32_e32 v177, 31, v176
	v_cvt_pk_bf16_f32 v172, v182, v183
	v_cvt_pk_bf16_f32 v173, v184, v185
	global_store_dwordx4 v[174:175], v[170:173], off offset:256
	v_lshlrev_b64 v[174:175], 13, v[176:177]
	v_lshl_add_u64 v[176:177], v[178:179], 0, v[158:159]
	v_lshl_add_u64 v[174:175], s[28:29], 0, v[174:175]
	v_lshl_add_u64 v[174:175], v[174:175], 0, v[156:157]
	s_waitcnt vmcnt(7)
	v_lshlrev_b32_e32 v3, 16, v218
	v_and_b32_e32 v5, 0xffff0000, v218
	v_lshlrev_b32_e32 v151, 16, v219
	v_and_b32_e32 v153, 0xffff0000, v219
	v_lshlrev_b32_e32 v155, 16, v220
	v_and_b32_e32 v161, 0xffff0000, v220
	v_lshlrev_b32_e32 v170, 16, v221
	v_and_b32_e32 v171, 0xffff0000, v221
	v_mul_f32_e32 v3, 0xbfb8aa3b, v3
	v_mul_f32_e32 v5, 0xbfb8aa3b, v5
	v_mul_f32_e32 v151, 0xbfb8aa3b, v151
	v_mul_f32_e32 v153, 0xbfb8aa3b, v153
	v_mul_f32_e32 v155, 0xbfb8aa3b, v155
	v_mul_f32_e32 v161, 0xbfb8aa3b, v161
	v_mul_f32_e32 v170, 0xbfb8aa3b, v170
	v_mul_f32_e32 v171, 0xbfb8aa3b, v171
	v_exp_f32_e32 v3, v3
	v_exp_f32_e32 v5, v5
	v_exp_f32_e32 v151, v151
	v_exp_f32_e32 v153, v153
	v_exp_f32_e32 v155, v155
	v_exp_f32_e32 v161, v161
	v_exp_f32_e32 v170, v170
	v_exp_f32_e32 v171, v171
	v_add_f32_e32 v3, 1.0, v3
	v_add_f32_e32 v5, 1.0, v5
	v_add_f32_e32 v151, 1.0, v151
	v_add_f32_e32 v153, 1.0, v153
	v_add_f32_e32 v155, 1.0, v155
	v_add_f32_e32 v161, 1.0, v161
	v_add_f32_e32 v179, 1.0, v170
	v_add_f32_e32 v181, 1.0, v171
	v_rcp_f32_e32 v170, v3
	v_rcp_f32_e32 v171, v5
	v_rcp_f32_e32 v172, v151
	v_rcp_f32_e32 v173, v153
	v_rcp_f32_e32 v178, v155
	v_rcp_f32_e32 v180, v179
	v_rcp_f32_e32 v181, v181
	v_rcp_f32_e32 v179, v161
	v_pk_mul_f32 v[172:173], v[52:53], v[172:173]
	v_pk_mul_f32 v[170:171], v[50:51], v[170:171]
	v_pk_mul_f32 v[180:181], v[48:49], v[180:181]
	v_pk_mul_f32 v[178:179], v[46:47], v[178:179]
	v_cvt_pk_bf16_f32 v170, v170, v171
	v_cvt_pk_bf16_f32 v171, v172, v173
	s_nop 0
	v_cvt_pk_bf16_f32 v172, v178, v179
	v_cvt_pk_bf16_f32 v173, v180, v181
	global_store_dwordx4 v[174:175], v[170:173], off
	v_add_u32_e32 v176, 0xb0, v4
	v_mad_i64_i32 v[166:167], s[38:39], v176, s73, v[166:167]
	v_lshl_add_u64 v[166:167], v[166:167], 0, s[14:15]
	v_lshl_add_u64 v[178:179], v[166:167], 0, v[156:157]
	v_lshl_add_u64 v[166:167], v[166:167], 0, v[158:159]
	s_waitcnt vmcnt(7)
	v_lshlrev_b32_e32 v3, 16, v222
	v_and_b32_e32 v5, 0xffff0000, v222
	v_lshlrev_b32_e32 v151, 16, v223
	v_and_b32_e32 v153, 0xffff0000, v223
	v_lshlrev_b32_e32 v155, 16, v224
	v_and_b32_e32 v161, 0xffff0000, v224
	v_lshlrev_b32_e32 v170, 16, v225
	v_and_b32_e32 v171, 0xffff0000, v225
	v_mul_f32_e32 v3, 0xbfb8aa3b, v3
	v_mul_f32_e32 v5, 0xbfb8aa3b, v5
	v_mul_f32_e32 v151, 0xbfb8aa3b, v151
	v_mul_f32_e32 v153, 0xbfb8aa3b, v153
	v_mul_f32_e32 v155, 0xbfb8aa3b, v155
	v_mul_f32_e32 v161, 0xbfb8aa3b, v161
	v_mul_f32_e32 v170, 0xbfb8aa3b, v170
	v_mul_f32_e32 v171, 0xbfb8aa3b, v171
	v_exp_f32_e32 v3, v3
	v_exp_f32_e32 v5, v5
	v_exp_f32_e32 v151, v151
	v_exp_f32_e32 v153, v153
	v_exp_f32_e32 v155, v155
	v_exp_f32_e32 v161, v161
	v_exp_f32_e32 v170, v170
	v_exp_f32_e32 v171, v171
	v_add_f32_e32 v3, 1.0, v3
	v_add_f32_e32 v5, 1.0, v5
	v_add_f32_e32 v151, 1.0, v151
	v_add_f32_e32 v153, 1.0, v153
	v_add_f32_e32 v155, 1.0, v155
	v_add_f32_e32 v161, 1.0, v161
	v_add_f32_e32 v177, 1.0, v170
	v_add_f32_e32 v181, 1.0, v171
	v_rcp_f32_e32 v170, v3
	v_rcp_f32_e32 v171, v5
	v_rcp_f32_e32 v172, v151
	v_rcp_f32_e32 v173, v153
	v_rcp_f32_e32 v180, v155
	v_rcp_f32_e32 v182, v177
	v_rcp_f32_e32 v183, v181
	v_rcp_f32_e32 v181, v161
	v_pk_mul_f32 v[172:173], v[20:21], v[172:173]
	v_pk_mul_f32 v[170:171], v[18:19], v[170:171]
	v_pk_mul_f32 v[182:183], v[16:17], v[182:183]
	v_pk_mul_f32 v[180:181], v[14:15], v[180:181]
	v_cvt_pk_bf16_f32 v170, v170, v171
	v_cvt_pk_bf16_f32 v171, v172, v173
	v_ashrrev_i32_e32 v177, 31, v176
	v_cvt_pk_bf16_f32 v172, v180, v181
	v_cvt_pk_bf16_f32 v173, v182, v183
	global_store_dwordx4 v[174:175], v[170:173], off offset:256
	v_lshlrev_b64 v[174:175], 13, v[176:177]
	v_lshl_add_u64 v[174:175], s[28:29], 0, v[174:175]
	v_lshl_add_u64 v[174:175], v[174:175], 0, v[156:157]
	s_waitcnt vmcnt(7)
	v_lshlrev_b32_e32 v3, 16, v226
	v_and_b32_e32 v5, 0xffff0000, v226
	v_lshlrev_b32_e32 v151, 16, v227
	v_and_b32_e32 v153, 0xffff0000, v227
	v_lshlrev_b32_e32 v155, 16, v228
	v_and_b32_e32 v156, 0xffff0000, v228
	v_lshlrev_b32_e32 v157, 16, v229
	v_and_b32_e32 v158, 0xffff0000, v229
	v_mul_f32_e32 v3, 0xbfb8aa3b, v3
	v_mul_f32_e32 v5, 0xbfb8aa3b, v5
	v_mul_f32_e32 v151, 0xbfb8aa3b, v151
	v_mul_f32_e32 v153, 0xbfb8aa3b, v153
	v_mul_f32_e32 v155, 0xbfb8aa3b, v155
	v_mul_f32_e32 v156, 0xbfb8aa3b, v156
	v_mul_f32_e32 v157, 0xbfb8aa3b, v157
	v_mul_f32_e32 v158, 0xbfb8aa3b, v158
	v_exp_f32_e32 v3, v3
	v_exp_f32_e32 v5, v5
	v_exp_f32_e32 v151, v151
	v_exp_f32_e32 v153, v153
	v_exp_f32_e32 v155, v155
	v_exp_f32_e32 v156, v156
	v_exp_f32_e32 v157, v157
	v_exp_f32_e32 v158, v158
	v_add_f32_e32 v3, 1.0, v3
	v_add_f32_e32 v5, 1.0, v5
	v_add_f32_e32 v151, 1.0, v151
	v_add_f32_e32 v153, 1.0, v153
	v_add_f32_e32 v155, 1.0, v155
	v_add_f32_e32 v161, 1.0, v156
	v_add_f32_e32 v171, 1.0, v157
	v_add_f32_e32 v173, 1.0, v158
	v_rcp_f32_e32 v156, v3
	v_rcp_f32_e32 v157, v5
	v_rcp_f32_e32 v158, v151
	v_rcp_f32_e32 v159, v153
	v_rcp_f32_e32 v170, v155
	v_rcp_f32_e32 v172, v171
	v_rcp_f32_e32 v173, v173
	v_rcp_f32_e32 v171, v161
	v_pk_mul_f32 v[158:159], v[44:45], v[158:159]
	v_pk_mul_f32 v[156:157], v[42:43], v[156:157]
	v_pk_mul_f32 v[172:173], v[40:41], v[172:173]
	v_pk_mul_f32 v[170:171], v[38:39], v[170:171]
	v_cvt_pk_bf16_f32 v156, v156, v157
	v_cvt_pk_bf16_f32 v157, v158, v159
	s_nop 0
	v_cvt_pk_bf16_f32 v158, v170, v171
	v_cvt_pk_bf16_f32 v159, v172, v173
	global_store_dwordx4 v[174:175], v[156:159], off
	s_waitcnt vmcnt(7)
	v_lshlrev_b32_e32 v3, 16, v230
	v_and_b32_e32 v5, 0xffff0000, v230
	v_lshlrev_b32_e32 v151, 16, v231
	v_and_b32_e32 v153, 0xffff0000, v231
	v_lshlrev_b32_e32 v155, 16, v232
	v_and_b32_e32 v156, 0xffff0000, v232
	v_lshlrev_b32_e32 v157, 16, v233
	v_and_b32_e32 v158, 0xffff0000, v233
	v_mul_f32_e32 v3, 0xbfb8aa3b, v3
	v_mul_f32_e32 v5, 0xbfb8aa3b, v5
	v_mul_f32_e32 v151, 0xbfb8aa3b, v151
	v_mul_f32_e32 v153, 0xbfb8aa3b, v153
	v_mul_f32_e32 v155, 0xbfb8aa3b, v155
	v_mul_f32_e32 v156, 0xbfb8aa3b, v156
	v_mul_f32_e32 v157, 0xbfb8aa3b, v157
	v_mul_f32_e32 v158, 0xbfb8aa3b, v158
	v_exp_f32_e32 v3, v3
	v_exp_f32_e32 v5, v5
	v_exp_f32_e32 v151, v151
	v_exp_f32_e32 v153, v153
	v_exp_f32_e32 v155, v155
	v_exp_f32_e32 v156, v156
	v_exp_f32_e32 v157, v157
	v_exp_f32_e32 v158, v158
	v_add_f32_e32 v3, 1.0, v3
	v_add_f32_e32 v5, 1.0, v5
	v_add_f32_e32 v151, 1.0, v151
	v_add_f32_e32 v153, 1.0, v153
	v_add_f32_e32 v155, 1.0, v155
	v_add_f32_e32 v161, 1.0, v156
	v_add_f32_e32 v167, 1.0, v157
	v_add_f32_e32 v171, 1.0, v158
	v_rcp_f32_e32 v156, v3
	v_rcp_f32_e32 v157, v5
	v_rcp_f32_e32 v158, v151
	v_rcp_f32_e32 v159, v153
	v_rcp_f32_e32 v166, v155
	v_rcp_f32_e32 v170, v167
	v_rcp_f32_e32 v171, v171
	v_rcp_f32_e32 v167, v161
	v_pk_mul_f32 v[158:159], v[12:13], v[158:159]
	v_pk_mul_f32 v[156:157], v[10:11], v[156:157]
	v_pk_mul_f32 v[170:171], v[8:9], v[170:171]
	v_pk_mul_f32 v[166:167], v[6:7], v[166:167]
	v_cvt_pk_bf16_f32 v156, v156, v157
	v_cvt_pk_bf16_f32 v157, v158, v159
	s_nop 0
	v_cvt_pk_bf16_f32 v158, v166, v167
	v_cvt_pk_bf16_f32 v159, v170, v171
	global_store_dwordx4 v[174:175], v[156:159], off offset:256
	s_cbranch_execnz .LBB0_1232
